# v37 + P3: odd workgroups run their sample-row GEMM item before the main unit (even after), staggering the HBM-bound residual epilogues
# speedup vs baseline: 1.0090x; 1.0004x over previous
.LBB0_303:
	s_mov_b32 s100, 0
	s_cmp_lt_i32 s76, 4
	s_cselect_b64 s[0:1], -1, 0
	s_add_u32 s4, s74, 0xe4000
	v_writelane_b32 v246, s4, 44
	s_addc_u32 s4, s75, 0
	s_and_b64 s[0:1], s[0:1], s[2:3]
	s_andn2_b64 vcc, exec, s[0:1]
	v_writelane_b32 v246, s4, 45
	s_cbranch_vccnz .LBB0_384
.Lsg3_redo:
	s_add_u32 s12, s74, 0xc00000
	s_addc_u32 s13, s75, 0
	s_add_u32 s10, s74, 0x2000
	s_addc_u32 s11, s75, 0
	s_cmp_eq_u32 s100, 2
	s_cbranch_scc1 .Lsg3_main
	s_cmpk_lg_i32 s78, 0x100
	s_cbranch_scc1 .Lsg3_main
	s_cmpk_gt_i32 s96, 0xff
	s_cbranch_scc1 .Lsg3_main
	s_bitcmp1_b32 s97, 0
	s_cbranch_scc0 .Lsg3_main
	s_mov_b32 s100, 1
	s_branch .LBB0_336
.Lsg3_main:
	s_cmpk_lt_i32 s96, 0x100
	s_cselect_b64 s[8:9], -1, 0
	s_cmpk_gt_i32 s96, 0xff
	v_readfirstlane_b32 s24, v236
	s_cbranch_scc1 .LBB0_336
	s_ashr_i32 s25, s96, 31
	s_lshr_b32 s2, s25, 29
	s_add_i32 s5, s96, s2
	s_and_b32 s2, s5, -8
	s_sub_i32 s6, s96, s2
	s_cmp_gt_i32 s6, -1
	s_cbranch_scc0 .LBB0_307
	s_lshl_b32 s4, s6, 5
	s_cbranch_execz .LBB0_308
	s_branch .LBB0_309

.LBB0_336:
	s_add_u32 s4, s72, 0x4000000
	s_addc_u32 s5, s73, 0
	v_mov_b32_e32 v0, v236
	s_cmp_eq_u32 s100, 2
	s_cbranch_scc1 .Lsg3_skip
	s_cmpk_gt_i32 s97, 0xff
	s_cbranch_scc1 .LBB0_339
	v_ashrrev_i32_e32 v7, 6, v0
	s_movk_i32 s2, 0x160
	v_mul_lo_u32 v2, v7, s2
	v_ashrrev_i32_e32 v3, 31, v2
	v_bfe_u32 v6, v0, 4, 2
	v_lshlrev_b64 v[2:3], 1, v[2:3]
	v_and_b32_e32 v54, 15, v0
	v_lshl_add_u64 v[4:5], s[74:75], 0, v[2:3]
	v_lshlrev_b32_e32 v36, 4, v6
	v_mov_b32_e32 v37, 0
	v_lshl_add_u64 v[2:3], s[12:13], 0, v[2:3]
	v_lshrrev_b32_e32 v1, 4, v0
	v_lshl_add_u64 v[40:41], v[2:3], 0, v[36:37]
	v_ashrrev_i32_e32 v55, 3, v0
	v_and_b32_e32 v0, 7, v0
	v_lshlrev_b32_e32 v2, 14, v7
	v_lshlrev_b32_e32 v3, 8, v54
	v_lshl_add_u64 v[4:5], v[4:5], 0, v[36:37]
	s_mov_b64 s[2:3], 0xb000000
	v_lshlrev_b32_e32 v56, 3, v0
	v_add3_u32 v2, 0, v2, v3
	v_lshlrev_b32_e32 v0, 1, v0
	v_and_b32_e32 v3, 15, v55
	v_lshl_add_u64 v[38:39], v[4:5], 0, s[2:3]
	v_bitop3_b32 v4, v0, v55, 15 bitop3:0x78
	v_bitop3_b32 v0, v0, v3, 1 bitop3:0x36
	v_lshl_add_u32 v3, v55, 8, 0
	v_bitop3_b32 v1, v1, v54, 3 bitop3:0x6c
	v_bitop3_b32 v5, v6, v54, 4 bitop3:0x36
	v_bitop3_b32 v7, v6, v54, 8 bitop3:0x36
	v_bitop3_b32 v6, v6, v54, 12 bitop3:0x36
	v_lshlrev_b32_e32 v4, 4, v4
	v_lshlrev_b32_e32 v0, 4, v0
	v_lshlrev_b32_e32 v1, 4, v1
	v_lshlrev_b32_e32 v5, 4, v5
	v_lshlrev_b32_e32 v7, 4, v7
	v_lshlrev_b32_e32 v6, 4, v6
	v_add_u32_e32 v8, 0x10000, v3
	v_add_u32_e32 v9, 0x14000, v3
	v_add_u32_e32 v10, 0x18000, v3
	v_add_u32_e32 v11, 0x1c000, v3
	v_readlane_b32 s36, v246, 21
	s_lshl_b32 s2, s97, 6
	s_lshl_b32 s3, s78, 6
	s_lshl_b32 s6, s97, 2
	s_lshl_b32 s7, s78, 2
	s_mov_b32 s12, 0x9000
	v_mov_b64_e32 v[42:43], s[10:11]
	s_movk_i32 s10, 0x1600
	s_mov_b32 s11, 0x16000
	s_mov_b32 s13, 0x2c000
	s_mov_b32 s14, 0x42000
	v_add_u32_e32 v57, v2, v1
	v_add_u32_e32 v58, v2, v5
	v_add_u32_e32 v59, v2, v7
	v_add_u32_e32 v60, v2, v6
	v_add_u32_e32 v61, v3, v4
	v_add_u32_e32 v62, v3, v0
	v_add_u32_e32 v63, v8, v4
	v_add_u32_e32 v64, v8, v0
	v_add_u32_e32 v65, v9, v4
	v_add_u32_e32 v66, v9, v0
	v_add_u32_e32 v67, v10, v4
	v_add_u32_e32 v68, v10, v0
	v_add_u32_e32 v69, v11, v4
	v_add_u32_e32 v70, v11, v0
	s_mov_b32 s15, s97
	v_readlane_b32 s38, v246, 23
	v_readlane_b32 s39, v246, 24
	v_readlane_b32 s37, v246, 22
	v_readlane_b32 s40, v246, 25
	v_readlane_b32 s41, v246, 26
	v_readlane_b32 s42, v246, 27
	v_readlane_b32 s43, v246, 28
	v_readlane_b32 s44, v246, 29
	v_readlane_b32 s45, v246, 30
	v_readlane_b32 s46, v246, 31
	v_readlane_b32 s47, v246, 32
	v_readlane_b32 s48, v246, 33
	v_readlane_b32 s49, v246, 34
	v_readlane_b32 s50, v246, 35
	v_readlane_b32 s51, v246, 36

.Lsg3_skip:
	v_readlane_b32 s42, v246, 27
	v_readlane_b32 s43, v246, 28
.LBB0_339:
	s_cmp_eq_u32 s100, 1
	s_cbranch_scc0 .Lsg3_cont
	s_mov_b32 s100, 2
	s_branch .Lsg3_redo
